# v86 + attention fast-loop barrier wait reduced to vmcnt(4) (LDS reads already drained by the PV step)
# speedup vs baseline: 1.0051x; 1.0024x over previous
.Latt_flA_top:
	s_waitcnt vmcnt(4)
	s_barrier
.Latt_flA_entry:
	s_lshl_b32 s6, s8, 14
	v_add_u32_e32 v228, s6, v163
	v_add_u32_e32 v229, s6, v164
	v_add_u32_e32 v230, s6, v165
	v_add_u32_e32 v231, s6, v166
	ds_read_b128 v[96:99], v228
	ds_read_b128 v[200:203], v229
	ds_read_b128 v[204:207], v230
	ds_read_b128 v[208:211], v231
	ds_read_b128 v[112:115], v228 offset:8192
	ds_read_b128 v[216:219], v229 offset:8192
	ds_read_b128 v[220:223], v230 offset:8192
	ds_read_b128 v[224:227], v231 offset:8192
	s_add_u32 s98, s0, s72
	s_addc_u32 s99, s1, s73
	s_lshl_b32 s4, s88, 14
	s_add_i32 s5, s87, s4
	s_mov_b32 m0, s5
	s_add_i32 s4, s95, 2
	s_and_b32 s4, s4, 3
	s_lshl_b32 s4, s4, 14
	s_add_i32 s4, s85, s4
	s_waitcnt lgkmcnt(7)
	v_mfma_f32_32x32x16_bf16 v[96:111], v[96:99], v[132:135], 0
	s_waitcnt lgkmcnt(6)
	v_mfma_f32_32x32x16_bf16 v[96:111], v[200:203], v[136:139], v[96:111]
	s_waitcnt lgkmcnt(5)
	v_mfma_f32_32x32x16_bf16 v[96:111], v[204:207], v[140:143], v[96:111]
	s_waitcnt lgkmcnt(4)
	v_mfma_f32_32x32x16_bf16 v[96:111], v[208:211], v[144:147], v[96:111]
	s_waitcnt lgkmcnt(3)
	v_mfma_f32_32x32x16_bf16 v[112:127], v[112:115], v[132:135], 0
	global_load_lds_dwordx4 v239, s[98:99]
	s_addk_i32 s5, 0x400
	s_mov_b32 m0, s5
	s_waitcnt lgkmcnt(2)
	v_mfma_f32_32x32x16_bf16 v[112:127], v[216:219], v[136:139], v[112:127]
	global_load_lds_dwordx4 v240, s[98:99]
	s_add_u32 s98, s66, s72
	s_addc_u32 s99, s67, s73
	s_mov_b32 m0, s4
	s_addk_i32 s4, 0x400
	s_waitcnt lgkmcnt(1)
	v_mfma_f32_32x32x16_bf16 v[112:127], v[220:223], v[140:143], v[112:127]
	global_load_lds_dwordx4 v241, s[98:99]
	s_mov_b32 m0, s4
	s_waitcnt lgkmcnt(0)
	v_mfma_f32_32x32x16_bf16 v[112:127], v[224:227], v[144:147], v[112:127]
	global_load_lds_dwordx4 v242, s[98:99]
	s_and_b32 s7, s95, 3
	s_lshl_b32 s7, s7, 14
	v_add_u32_e32 v243, s7, v7
	v_add_u32_e32 v244, s7, v9
	v_add_u32_e32 v245, s7, v10
	v_add_u32_e32 v246, s7, v11
	ds_read_b64_tr_b16 v[188:189], v243 offset:49152
	ds_read_b64_tr_b16 v[190:191], v243 offset:51200
	ds_read_b64_tr_b16 v[192:193], v244
	ds_read_b64_tr_b16 v[194:195], v244 offset:2048
	ds_read_b64_tr_b16 v[196:197], v245
	ds_read_b64_tr_b16 v[198:199], v245 offset:2048
	ds_read_b64_tr_b16 v[200:201], v246
	ds_read_b64_tr_b16 v[202:203], v246 offset:2048
	v_exp_f32_e32 v228, v96
	v_exp_f32_e32 v229, v97
	v_exp_f32_e32 v230, v98
	v_exp_f32_e32 v231, v99
	v_exp_f32_e32 v232, v100
	v_exp_f32_e32 v233, v101
	v_exp_f32_e32 v234, v102
	v_exp_f32_e32 v187, v103
	v_cvt_pk_bf16_f32 v220, v228, v229
	v_cvt_pk_bf16_f32 v221, v230, v231
	v_cvt_pk_bf16_f32 v222, v232, v233
	v_cvt_pk_bf16_f32 v223, v234, v187
	ds_read_b64_tr_b16 v[204:205], v243 offset:53248
	ds_read_b64_tr_b16 v[206:207], v243 offset:55296
	ds_read_b64_tr_b16 v[208:209], v244 offset:4096
	ds_read_b64_tr_b16 v[210:211], v244 offset:6144
	ds_read_b64_tr_b16 v[212:213], v245 offset:4096
	ds_read_b64_tr_b16 v[214:215], v245 offset:6144
	ds_read_b64_tr_b16 v[216:217], v246 offset:4096
	ds_read_b64_tr_b16 v[218:219], v246 offset:6144
	s_waitcnt lgkmcnt(8)
	v_mfma_f32_32x32x16_bf16 v[80:95], v[188:191], v[220:223], v[80:95]
	ds_read_b64_tr_b16 v[188:189], v243 offset:57344
	ds_read_b64_tr_b16 v[190:191], v243 offset:59392
	v_exp_f32_e32 v247, v104
	v_exp_f32_e32 v248, v105
	v_add_f32_e32 v153, 0, v228
	v_add_f32_e32 v153, v229, v153
	v_mfma_f32_32x32x16_bf16 v[64:79], v[192:195], v[220:223], v[64:79]
	ds_read_b64_tr_b16 v[192:193], v244 offset:8192
	ds_read_b64_tr_b16 v[194:195], v244 offset:10240
	v_exp_f32_e32 v249, v106
	v_exp_f32_e32 v250, v107
	v_add_f32_e32 v153, v230, v153
	v_add_f32_e32 v153, v231, v153
	v_mfma_f32_32x32x16_bf16 v[48:63], v[196:199], v[220:223], v[48:63]
	ds_read_b64_tr_b16 v[196:197], v245 offset:8192
	ds_read_b64_tr_b16 v[198:199], v245 offset:10240
	v_exp_f32_e32 v251, v108
	v_exp_f32_e32 v252, v109
	v_add_f32_e32 v153, v232, v153
	v_add_f32_e32 v153, v233, v153
	v_mfma_f32_32x32x16_bf16 v[32:47], v[200:203], v[220:223], v[32:47]
	ds_read_b64_tr_b16 v[200:201], v246 offset:8192
	ds_read_b64_tr_b16 v[202:203], v246 offset:10240
	v_exp_f32_e32 v253, v110
	v_exp_f32_e32 v254, v111
	v_cvt_pk_bf16_f32 v224, v247, v248
	v_cvt_pk_bf16_f32 v225, v249, v250
	v_cvt_pk_bf16_f32 v226, v251, v252
	v_cvt_pk_bf16_f32 v227, v253, v254
	v_add_f32_e32 v153, v234, v153
	v_add_f32_e32 v153, v187, v153
	s_waitcnt lgkmcnt(8)
	v_mfma_f32_32x32x16_bf16 v[80:95], v[204:207], v[224:227], v[80:95]
	ds_read_b64_tr_b16 v[204:205], v243 offset:61440
	ds_read_b64_tr_b16 v[206:207], v243 offset:63488
	v_exp_f32_e32 v228, v112
	v_exp_f32_e32 v229, v113
	v_add_f32_e32 v153, v247, v153
	v_add_f32_e32 v153, v248, v153
	v_mfma_f32_32x32x16_bf16 v[64:79], v[208:211], v[224:227], v[64:79]
	ds_read_b64_tr_b16 v[208:209], v244 offset:12288
	ds_read_b64_tr_b16 v[210:211], v244 offset:14336
	v_exp_f32_e32 v230, v114
	v_exp_f32_e32 v231, v115
	v_add_f32_e32 v153, v249, v153
	v_add_f32_e32 v153, v250, v153
	v_mfma_f32_32x32x16_bf16 v[48:63], v[212:215], v[224:227], v[48:63]
	ds_read_b64_tr_b16 v[212:213], v245 offset:12288
	ds_read_b64_tr_b16 v[214:215], v245 offset:14336
	v_exp_f32_e32 v232, v116
	v_exp_f32_e32 v233, v117
	v_add_f32_e32 v153, v251, v153
	v_add_f32_e32 v153, v252, v153
	v_mfma_f32_32x32x16_bf16 v[32:47], v[216:219], v[224:227], v[32:47]
	ds_read_b64_tr_b16 v[216:217], v246 offset:12288
	ds_read_b64_tr_b16 v[218:219], v246 offset:14336
	v_exp_f32_e32 v234, v118
	v_exp_f32_e32 v187, v119
	v_cvt_pk_bf16_f32 v220, v228, v229
	v_cvt_pk_bf16_f32 v221, v230, v231
	v_cvt_pk_bf16_f32 v222, v232, v233
	v_cvt_pk_bf16_f32 v223, v234, v187
	v_add_f32_e32 v153, v253, v153
	v_add_f32_e32 v153, v254, v153
	s_waitcnt lgkmcnt(8)
	v_mfma_f32_32x32x16_bf16 v[80:95], v[188:191], v[220:223], v[80:95]
	v_exp_f32_e32 v247, v120
	v_exp_f32_e32 v248, v121
	v_add_f32_e32 v153, v228, v153
	v_add_f32_e32 v153, v229, v153
	v_mfma_f32_32x32x16_bf16 v[64:79], v[192:195], v[220:223], v[64:79]
	v_exp_f32_e32 v249, v122
	v_exp_f32_e32 v250, v123
	v_add_f32_e32 v153, v230, v153
	v_add_f32_e32 v153, v231, v153
	v_mfma_f32_32x32x16_bf16 v[48:63], v[196:199], v[220:223], v[48:63]
	v_exp_f32_e32 v251, v124
	v_exp_f32_e32 v252, v125
	v_add_f32_e32 v153, v232, v153
	v_add_f32_e32 v153, v233, v153
	v_mfma_f32_32x32x16_bf16 v[32:47], v[200:203], v[220:223], v[32:47]
	v_exp_f32_e32 v253, v126
	v_exp_f32_e32 v254, v127
	v_cvt_pk_bf16_f32 v224, v247, v248
	v_cvt_pk_bf16_f32 v225, v249, v250
	v_cvt_pk_bf16_f32 v226, v251, v252
	v_cvt_pk_bf16_f32 v227, v253, v254
	v_add_f32_e32 v153, v234, v153
	v_add_f32_e32 v153, v187, v153
	s_waitcnt lgkmcnt(0)
	v_mfma_f32_32x32x16_bf16 v[80:95], v[204:207], v[224:227], v[80:95]
	v_add_f32_e32 v153, v247, v153
	v_add_f32_e32 v153, v248, v153
	v_mfma_f32_32x32x16_bf16 v[64:79], v[208:211], v[224:227], v[64:79]
	v_add_f32_e32 v153, v249, v153
	v_add_f32_e32 v153, v250, v153
	v_mfma_f32_32x32x16_bf16 v[48:63], v[212:215], v[224:227], v[48:63]
	v_add_f32_e32 v153, v251, v153
	v_add_f32_e32 v153, v252, v153
	v_mfma_f32_32x32x16_bf16 v[32:47], v[216:219], v[224:227], v[32:47]
	v_add_f32_e32 v153, v253, v153
	v_add_f32_e32 v153, v254, v153
	v_add_f32_e32 v6, v6, v153
	s_add_u32 s72, s72, 0x20000
	s_addc_u32 s73, s73, 0
	s_add_i32 s95, s95, 1
	s_mov_b32 s71, s8
	s_mov_b32 s8, s78
	s_mov_b32 s78, s88
	s_mov_b32 s88, s71
	s_sub_i32 s101, s101, 1
	s_cmp_lg_u32 s101, 0
	s_cbranch_scc1 .Latt_flA_top
	s_waitcnt vmcnt(4)
	s_barrier
	s_lshl_b32 s4, s100, 6
	s_sub_i32 s33, s33, s4
	s_sub_i32 s93, s93, s4
	s_sub_u32 s90, s90, s4
	s_subb_u32 s91, s91, 0
	v_add_u32_e32 v179, s4, v179
	s_branch .Latt_slow
